# adds: nsa_norm_rows 4 row loads in flight, transpose item rotation, GLA gate-stage z-row LDS reads prefetched through 6 free quads
# speedup vs baseline: 1.0108x; 1.0078x over previous
; DI int TIDX() { int t = (int)threadIdx.x; asm volatile("" : "+v"(t)); return t; }
; DI int BIDX() { int t = (int)blockIdx.x; asm volatile("" : "+s"(t)); return t; }
; DI int GDIM() { int t = (int)gridDim.x; asm volatile("" : "+s"(t)); return t; }
; DI void transpose_item(const float* W, int K, int N, int Npad, bf16_t* WT, int item, float* scr, int lane) {
;   const int nblk = Npad / 64, kb = item / nblk, nb = item % nblk, k0 = 64 * kb, n0 = 64 * nb;
;   const int nn = n0 + lane; const bool okn = nn < N;
;   const float* wp = W + (size_t)k0 * N + (okn ? nn : 0);
; DI void prologue(const KP& p, float* lds) {
;   const int tid = TIDX(), lane = tid & 63, wave = tid >> 6, G = GDIM();
;     ...
;   for (int rep = 0; rep < EXP_REPA; ++rep)
;   for (int it = BIDX(); it < 386; it += G) { if (it < 384) ada_item(p, it, lds); else posb_item(p, it - 384, lds); }
;   __syncthreads();
;   float* scr = lds + wave * (64 * 65);
;   const int gw = BIDX() * 8 + wave, NGW = G * 8;
;   unsigned char* ws = p.ws;
;   constexpr int I_ABIN = 32 * (LDP0 / 64), I_SQ = 32 * 32, I_W1 = 32 * 128, I_W2 = 128 * 32, I_MLIN = 32 * (LDP1 / 64), I_C1 = 32, I_C2 = 1;
;   constexpr int NITEMS = I_ABIN + I_SQ + 2 * I_W1 + 2 * I_W2 + I_MLIN + I_SQ + 2 * I_C1 + 2 * I_C2;
;   for (int it = gw; it < NITEMS; it += NGW) {
.LBB0_32:
	v_readlane_b32 s2, v252, 0
	s_add_i32 s3, s2, 0x7e
	s_and_b32 s3, s3, 0xff
	s_cmpk_eq_u32 s14, 0x100
	s_cselect_b32 s2, s3, s2
	v_ashrrev_i32_e32 v2, 6, v104
	s_waitcnt lgkmcnt(0)
	s_barrier
	s_nop 0
	v_lshl_add_u32 v1, s2, 3, v2
	s_movk_i32 s2, 0x6042
	v_cmp_gt_i32_e32 vcc, s2, v1
	s_and_saveexec_b64 s[2:3], vcc
	s_cbranch_execz .LBB0_71
	s_movk_i32 s4, 0x4100
	v_mul_lo_u32 v2, v2, s4
	v_add_u32_e32 v4, 32, v2
	v_lshlrev_b32_e32 v2, 3, v104
	v_and_b32_e32 v2, 56, v2
	v_lshlrev_b32_e32 v168, 1, v2
	v_bfe_u32 v39, v104, 3, 3
	v_lshl_add_u64 v[50:51], s[6:7], 0, v[168:169]
	s_mov_b64 s[4:5], 0x208400
	v_lshl_add_u64 v[18:19], v[50:51], 0, s[4:5]
	v_or_b32_e32 v53, 8, v39
	v_or_b32_e32 v55, 16, v39
	v_or_b32_e32 v57, 24, v39
	v_or_b32_e32 v59, 32, v39
	v_or_b32_e32 v61, 40, v39
	v_or_b32_e32 v63, 48, v39
	v_or_b32_e32 v70, 56, v39
	s_mov_b64 s[4:5], 0x20a400
	v_and_b32_e32 v0, 63, v104
	v_mul_u32_u24_e32 v5, 0x104, v2
	v_lshlrev_b32_e32 v6, 2, v39
	v_lshlrev_b32_e32 v168, 7, v39
	v_lshlrev_b32_e32 v22, 7, v53
	v_mov_b32_e32 v23, v169
	v_lshlrev_b32_e32 v24, 7, v55
	v_mov_b32_e32 v25, v169
	v_lshlrev_b32_e32 v26, 7, v57
	v_mov_b32_e32 v27, v169
	v_lshlrev_b32_e32 v28, 7, v59
	v_mov_b32_e32 v29, v169
	v_lshlrev_b32_e32 v30, 7, v61
	v_mov_b32_e32 v31, v169
	v_lshlrev_b32_e32 v32, 7, v63
	v_mov_b32_e32 v33, v169
	v_lshlrev_b32_e32 v34, 7, v70
	v_mov_b32_e32 v35, v169
	v_lshl_add_u64 v[36:37], v[50:51], 0, s[4:5]
	s_mov_b64 s[4:5], 0x1c8400
	v_lshl_add_u32 v3, v0, 2, v4
	v_add3_u32 v41, v4, v5, v6
	v_lshl_add_u64 v[4:5], v[18:19], 0, v[168:169]
	v_lshl_add_u64 v[6:7], v[18:19], 0, v[22:23]
	v_lshl_add_u64 v[8:9], v[18:19], 0, v[24:25]
	v_lshl_add_u64 v[10:11], v[18:19], 0, v[26:27]
	v_lshl_add_u64 v[12:13], v[18:19], 0, v[28:29]
	v_lshl_add_u64 v[14:15], v[18:19], 0, v[30:31]
	v_lshl_add_u64 v[16:17], v[18:19], 0, v[32:33]
	v_lshl_add_u64 v[18:19], v[18:19], 0, v[34:35]
	v_lshl_add_u64 v[20:21], v[36:37], 0, v[168:169]
	v_lshl_add_u64 v[22:23], v[36:37], 0, v[22:23]
	v_lshl_add_u64 v[24:25], v[36:37], 0, v[24:25]
	v_lshl_add_u64 v[26:27], v[36:37], 0, v[26:27]
	v_lshl_add_u64 v[28:29], v[36:37], 0, v[28:29]
	v_lshl_add_u64 v[30:31], v[36:37], 0, v[30:31]
	v_lshl_add_u64 v[32:33], v[36:37], 0, v[32:33]
	v_lshl_add_u64 v[34:35], v[36:37], 0, v[34:35]
	v_lshl_add_u64 v[36:37], v[50:51], 0, s[4:5]
	s_mov_b64 s[4:5], 0x188400
	s_lshl_b32 s28, s14, 3
	v_lshl_add_u64 v[42:43], v[50:51], 0, s[4:5]
	s_mov_b64 s[4:5], 0xba0c400
	v_lshl_add_u64 v[44:45], v[50:51], 0, s[4:5]
	s_mov_b64 s[4:5], 0xa10c400
	s_add_u32 s8, s6, 0x610c400
	v_lshl_add_u64 v[46:47], v[50:51], 0, s[4:5]
	s_addc_u32 s9, s7, 0
	s_mov_b64 s[4:5], 0x190c400
	s_add_u32 s10, s6, 0x210c400
	v_lshl_add_u64 v[48:49], v[50:51], 0, s[4:5]
	s_mov_b64 s[4:5], 0x20c400
	v_mov_b32_e32 v52, 0x14800
	v_mov_b32_e32 v64, 0xffe7f800
	v_lshlrev_b32_e32 v38, 11, v39
	v_lshlrev_b32_e32 v40, 11, v53
	s_addc_u32 s11, s7, 0
	v_lshl_add_u64 v[50:51], v[50:51], 0, s[4:5]
	s_lshl_b32 s29, s14, 9
	v_lshl_add_u32 v71, v1, 1, v52
	s_lshl_b32 s30, s14, 4
	s_mov_b64 s[12:13], 0
	v_lshlrev_b32_e32 v52, 11, v55
	v_lshlrev_b32_e32 v54, 11, v57
	v_lshlrev_b32_e32 v56, 11, v59
	v_lshlrev_b32_e32 v58, 11, v61
	v_lshlrev_b32_e32 v60, 11, v63
	v_lshlrev_b32_e32 v62, 11, v70
	v_lshl_add_u32 v64, v1, 6, v64
	s_branch .LBB0_35

; DI unsigned pk2(float a, float b) { const f32x2_t f = {a, b}; const bf16x2_t r = __builtin_convertvector(f, bf16x2_t); return __builtin_bit_cast(unsigned, r); }
; DI void nsa_norm_rows(const KP& p, bf16_t* proj) {
;     ...
;   for (int job = gt >> 3; job < njob; job += stride) {
;     const int tok = job >> 3, slot = job & 7;
;     const int col = slot < 4 ? N_KS + slot * 64 : N_KW + (slot - 4) * 64;
;     bf16_t* ptr = proj + (size_t)tok * LDP0 + col + sub * 8;
;     float v[8]; unpack8(*(const u32x4*)ptr, v);
;     float ss = 0.f;
; #pragma unroll
;     for (int i = 0; i < 8; ++i) ss += v[i] * v[i];
;     ss += __shfl_xor(ss, 1); ss += __shfl_xor(ss, 2); ss += __shfl_xor(ss, 4);
;     const float rstd = rsqrtf(ss * (1.f / 64.f) + EPS);
;     float y[8];
; #pragma unroll
;     for (int i = 0; i < 8; ++i) y[i] = v[i] * rstd * gk[i];
;     u32x4 w; w.x = pk2(y[0], y[1]); w.y = pk2(y[2], y[3]); w.z = pk2(y[4], y[5]); w.w = pk2(y[6], y[7]);
;     *(u32x4*)ptr = w;
.LBB0_335:
	v_ashrrev_i32_e32 v14, 3, v10
	v_mad_i64_i32 v[48:49], s[6:7], v14, s97, v[8:9]
	global_load_dwordx4 v[32:35], v[48:49], off
	v_add_u32_e32 v10, s2, v10
	v_ashrrev_i32_e32 v14, 3, v10
	v_mad_i64_i32 v[50:51], s[6:7], v14, s97, v[8:9]
	global_load_dwordx4 v[36:39], v[50:51], off
	v_add_u32_e32 v10, s2, v10
	v_ashrrev_i32_e32 v14, 3, v10
	v_mad_i64_i32 v[52:53], s[6:7], v14, s97, v[8:9]
	global_load_dwordx4 v[40:43], v[52:53], off
	v_add_u32_e32 v10, s2, v10
	v_ashrrev_i32_e32 v14, 3, v10
	v_mad_i64_i32 v[54:55], s[6:7], v14, s97, v[8:9]
	global_load_dwordx4 v[44:47], v[54:55], off
	v_add_u32_e32 v10, s2, v10
	s_mov_b32 s3, 0x3ffff
	v_cmp_lt_i32_e32 vcc, s3, v10
	s_or_b64 s[0:1], vcc, s[0:1]
	s_waitcnt vmcnt(3)
	v_mov_b32_e32 v18, v48
	v_mov_b32_e32 v19, v49
	v_mov_b32_e32 v14, v32
	v_mov_b32_e32 v15, v33
	v_mov_b32_e32 v16, v34
	v_mov_b32_e32 v17, v35
	v_lshlrev_b32_e32 v24, 16, v14
	v_and_b32_e32 v25, 0xffff0000, v14
	v_lshlrev_b32_e32 v20, 16, v17
	v_and_b32_e32 v21, 0xffff0000, v17
	v_lshlrev_b32_e32 v22, 16, v16
	v_and_b32_e32 v23, 0xffff0000, v16
	v_lshlrev_b32_e32 v16, 16, v15
	v_and_b32_e32 v17, 0xffff0000, v15
	v_pk_mul_f32 v[30:31], v[24:25], v[24:25]
	v_pk_mul_f32 v[28:29], v[16:17], v[16:17]
	v_add_f32_e32 v30, v30, v31
	v_add_f32_e32 v28, v28, v30
	v_pk_mul_f32 v[26:27], v[22:23], v[22:23]
	v_add_f32_e32 v28, v29, v28
	v_add_f32_e32 v26, v26, v28
	v_pk_mul_f32 v[14:15], v[20:21], v[20:21]
	v_add_f32_e32 v26, v27, v26
	v_add_f32_e32 v14, v14, v26
	v_add_f32_e32 v14, v15, v14
	ds_bpermute_b32 v15, v11, v14
	s_waitcnt lgkmcnt(0)
	v_add_f32_e32 v14, v14, v15
	ds_bpermute_b32 v15, v12, v14
	s_waitcnt lgkmcnt(0)
	v_add_f32_e32 v14, v14, v15
	ds_bpermute_b32 v15, v13, v14
	s_waitcnt lgkmcnt(0)
	v_add_f32_e32 v14, v14, v15
	v_fmamk_f32 v14, v14, 0x3c800000, v198
	v_mul_f32_e32 v15, 0x4b800000, v14
	v_cmp_gt_f32_e32 vcc, s92, v14
	s_nop 1
	v_cndmask_b32_e32 v14, v14, v15, vcc
	v_rsq_f32_e32 v14, v14
	s_nop 0
	v_mul_f32_e32 v15, 0x45800000, v14
	v_cndmask_b32_e32 v14, v14, v15, vcc
	v_pk_mul_f32 v[24:25], v[14:15], v[24:25] op_sel_hi:[0,1]
	v_pk_mul_f32 v[16:17], v[14:15], v[16:17] op_sel_hi:[0,1]
	v_pk_mul_f32 v[22:23], v[14:15], v[22:23] op_sel_hi:[0,1]
	v_pk_mul_f32 v[14:15], v[14:15], v[20:21] op_sel_hi:[0,1]
	v_pk_mul_f32 v[20:21], v[4:5], v[24:25]
	v_pk_mul_f32 v[16:17], v[6:7], v[16:17]
	v_pk_mul_f32 v[22:23], v[0:1], v[22:23]
	v_pk_mul_f32 v[24:25], v[2:3], v[14:15]
	v_cvt_pk_bf16_f32 v14, v20, v21
	v_cvt_pk_bf16_f32 v15, v16, v17
	v_cvt_pk_bf16_f32 v16, v22, v23
	v_cvt_pk_bf16_f32 v17, v24, v25
	global_store_dwordx4 v[18:19], v[14:17], off
	s_waitcnt vmcnt(3)
	v_mov_b32_e32 v18, v50
	v_mov_b32_e32 v19, v51
	v_mov_b32_e32 v14, v36
	v_mov_b32_e32 v15, v37
	v_mov_b32_e32 v16, v38
	v_mov_b32_e32 v17, v39
	v_lshlrev_b32_e32 v24, 16, v14
	v_and_b32_e32 v25, 0xffff0000, v14
	v_lshlrev_b32_e32 v20, 16, v17
	v_and_b32_e32 v21, 0xffff0000, v17
	v_lshlrev_b32_e32 v22, 16, v16
	v_and_b32_e32 v23, 0xffff0000, v16
	v_lshlrev_b32_e32 v16, 16, v15
	v_and_b32_e32 v17, 0xffff0000, v15
	v_pk_mul_f32 v[30:31], v[24:25], v[24:25]
	v_pk_mul_f32 v[28:29], v[16:17], v[16:17]
	v_add_f32_e32 v30, v30, v31
	v_add_f32_e32 v28, v28, v30
	v_pk_mul_f32 v[26:27], v[22:23], v[22:23]
	v_add_f32_e32 v28, v29, v28
	v_add_f32_e32 v26, v26, v28
	v_pk_mul_f32 v[14:15], v[20:21], v[20:21]
	v_add_f32_e32 v26, v27, v26
	v_add_f32_e32 v14, v14, v26
	v_add_f32_e32 v14, v15, v14
	ds_bpermute_b32 v15, v11, v14
	s_waitcnt lgkmcnt(0)
	v_add_f32_e32 v14, v14, v15
	ds_bpermute_b32 v15, v12, v14
	s_waitcnt lgkmcnt(0)
	v_add_f32_e32 v14, v14, v15
	ds_bpermute_b32 v15, v13, v14
	s_waitcnt lgkmcnt(0)
	v_add_f32_e32 v14, v14, v15
	v_fmamk_f32 v14, v14, 0x3c800000, v198
	v_mul_f32_e32 v15, 0x4b800000, v14
	v_cmp_gt_f32_e32 vcc, s92, v14
	s_nop 1
	v_cndmask_b32_e32 v14, v14, v15, vcc
	v_rsq_f32_e32 v14, v14
	s_nop 0
	v_mul_f32_e32 v15, 0x45800000, v14
	v_cndmask_b32_e32 v14, v14, v15, vcc
	v_pk_mul_f32 v[24:25], v[14:15], v[24:25] op_sel_hi:[0,1]
	v_pk_mul_f32 v[16:17], v[14:15], v[16:17] op_sel_hi:[0,1]
	v_pk_mul_f32 v[22:23], v[14:15], v[22:23] op_sel_hi:[0,1]
	v_pk_mul_f32 v[14:15], v[14:15], v[20:21] op_sel_hi:[0,1]
	v_pk_mul_f32 v[20:21], v[4:5], v[24:25]
	v_pk_mul_f32 v[16:17], v[6:7], v[16:17]
	v_pk_mul_f32 v[22:23], v[0:1], v[22:23]
	v_pk_mul_f32 v[24:25], v[2:3], v[14:15]
	v_cvt_pk_bf16_f32 v14, v20, v21
	v_cvt_pk_bf16_f32 v15, v16, v17
	v_cvt_pk_bf16_f32 v16, v22, v23
	v_cvt_pk_bf16_f32 v17, v24, v25
	global_store_dwordx4 v[18:19], v[14:17], off
	s_waitcnt vmcnt(3)
; DI unsigned pk2(float a, float b) { const f32x2_t f = {a, b}; const bf16x2_t r = __builtin_convertvector(f, bf16x2_t); return __builtin_bit_cast(unsigned, r); }
; DI void nsa_norm_rows(const KP& p, bf16_t* proj) {
;     ...
;   for (int job = gt >> 3; job < njob; job += stride) {
;     const int tok = job >> 3, slot = job & 7;
;     const int col = slot < 4 ? N_KS + slot * 64 : N_KW + (slot - 4) * 64;
;     bf16_t* ptr = proj + (size_t)tok * LDP0 + col + sub * 8;
;     float v[8]; unpack8(*(const u32x4*)ptr, v);
;     float ss = 0.f;
; #pragma unroll
;     for (int i = 0; i < 8; ++i) ss += v[i] * v[i];
;     ss += __shfl_xor(ss, 1); ss += __shfl_xor(ss, 2); ss += __shfl_xor(ss, 4);
;     const float rstd = rsqrtf(ss * (1.f / 64.f) + EPS);
;     float y[8];
; #pragma unroll
;     for (int i = 0; i < 8; ++i) y[i] = v[i] * rstd * gk[i];
;     u32x4 w; w.x = pk2(y[0], y[1]); w.y = pk2(y[2], y[3]); w.z = pk2(y[4], y[5]); w.w = pk2(y[6], y[7]);
;     *(u32x4*)ptr = w;
	v_mov_b32_e32 v18, v52
	v_mov_b32_e32 v19, v53
	v_mov_b32_e32 v14, v40
	v_mov_b32_e32 v15, v41
	v_mov_b32_e32 v16, v42
	v_mov_b32_e32 v17, v43
	v_lshlrev_b32_e32 v24, 16, v14
	v_and_b32_e32 v25, 0xffff0000, v14
	v_lshlrev_b32_e32 v20, 16, v17
	v_and_b32_e32 v21, 0xffff0000, v17
	v_lshlrev_b32_e32 v22, 16, v16
	v_and_b32_e32 v23, 0xffff0000, v16
	v_lshlrev_b32_e32 v16, 16, v15
	v_and_b32_e32 v17, 0xffff0000, v15
	v_pk_mul_f32 v[30:31], v[24:25], v[24:25]
	v_pk_mul_f32 v[28:29], v[16:17], v[16:17]
	v_add_f32_e32 v30, v30, v31
	v_add_f32_e32 v28, v28, v30
	v_pk_mul_f32 v[26:27], v[22:23], v[22:23]
	v_add_f32_e32 v28, v29, v28
	v_add_f32_e32 v26, v26, v28
	v_pk_mul_f32 v[14:15], v[20:21], v[20:21]
	v_add_f32_e32 v26, v27, v26
	v_add_f32_e32 v14, v14, v26
	v_add_f32_e32 v14, v15, v14
	ds_bpermute_b32 v15, v11, v14
	s_waitcnt lgkmcnt(0)
	v_add_f32_e32 v14, v14, v15
	ds_bpermute_b32 v15, v12, v14
	s_waitcnt lgkmcnt(0)
	v_add_f32_e32 v14, v14, v15
	ds_bpermute_b32 v15, v13, v14
	s_waitcnt lgkmcnt(0)
	v_add_f32_e32 v14, v14, v15
	v_fmamk_f32 v14, v14, 0x3c800000, v198
	v_mul_f32_e32 v15, 0x4b800000, v14
	v_cmp_gt_f32_e32 vcc, s92, v14
	s_nop 1
	v_cndmask_b32_e32 v14, v14, v15, vcc
	v_rsq_f32_e32 v14, v14
	s_nop 0
	v_mul_f32_e32 v15, 0x45800000, v14
	v_cndmask_b32_e32 v14, v14, v15, vcc
	v_pk_mul_f32 v[24:25], v[14:15], v[24:25] op_sel_hi:[0,1]
	v_pk_mul_f32 v[16:17], v[14:15], v[16:17] op_sel_hi:[0,1]
	v_pk_mul_f32 v[22:23], v[14:15], v[22:23] op_sel_hi:[0,1]
	v_pk_mul_f32 v[14:15], v[14:15], v[20:21] op_sel_hi:[0,1]
	v_pk_mul_f32 v[20:21], v[4:5], v[24:25]
	v_pk_mul_f32 v[16:17], v[6:7], v[16:17]
	v_pk_mul_f32 v[22:23], v[0:1], v[22:23]
	v_pk_mul_f32 v[24:25], v[2:3], v[14:15]
	v_cvt_pk_bf16_f32 v14, v20, v21
	v_cvt_pk_bf16_f32 v15, v16, v17
	v_cvt_pk_bf16_f32 v16, v22, v23
	v_cvt_pk_bf16_f32 v17, v24, v25
	global_store_dwordx4 v[18:19], v[14:17], off
	s_waitcnt vmcnt(3)
	v_mov_b32_e32 v18, v54
	v_mov_b32_e32 v19, v55
	v_mov_b32_e32 v14, v44
	v_mov_b32_e32 v15, v45
	v_mov_b32_e32 v16, v46
	v_mov_b32_e32 v17, v47
	v_lshlrev_b32_e32 v24, 16, v14
	v_and_b32_e32 v25, 0xffff0000, v14
	v_lshlrev_b32_e32 v20, 16, v17
	v_and_b32_e32 v21, 0xffff0000, v17
	v_lshlrev_b32_e32 v22, 16, v16
	v_and_b32_e32 v23, 0xffff0000, v16
	v_lshlrev_b32_e32 v16, 16, v15
	v_and_b32_e32 v17, 0xffff0000, v15
	v_pk_mul_f32 v[30:31], v[24:25], v[24:25]
	v_pk_mul_f32 v[28:29], v[16:17], v[16:17]
	v_add_f32_e32 v30, v30, v31
	v_add_f32_e32 v28, v28, v30
	v_pk_mul_f32 v[26:27], v[22:23], v[22:23]
	v_add_f32_e32 v28, v29, v28
	v_add_f32_e32 v26, v26, v28
	v_pk_mul_f32 v[14:15], v[20:21], v[20:21]
	v_add_f32_e32 v26, v27, v26
	v_add_f32_e32 v14, v14, v26
	v_add_f32_e32 v14, v15, v14
	ds_bpermute_b32 v15, v11, v14
	s_waitcnt lgkmcnt(0)
	v_add_f32_e32 v14, v14, v15
	ds_bpermute_b32 v15, v12, v14
	s_waitcnt lgkmcnt(0)
	v_add_f32_e32 v14, v14, v15
	ds_bpermute_b32 v15, v13, v14
	s_waitcnt lgkmcnt(0)
	v_add_f32_e32 v14, v14, v15
	v_fmamk_f32 v14, v14, 0x3c800000, v198
	v_mul_f32_e32 v15, 0x4b800000, v14
	v_cmp_gt_f32_e32 vcc, s92, v14
	s_nop 1
	v_cndmask_b32_e32 v14, v14, v15, vcc
	v_rsq_f32_e32 v14, v14
	s_nop 0
	v_mul_f32_e32 v15, 0x45800000, v14
	v_cndmask_b32_e32 v14, v14, v15, vcc
	v_pk_mul_f32 v[24:25], v[14:15], v[24:25] op_sel_hi:[0,1]
	v_pk_mul_f32 v[16:17], v[14:15], v[16:17] op_sel_hi:[0,1]
	v_pk_mul_f32 v[22:23], v[14:15], v[22:23] op_sel_hi:[0,1]
	v_pk_mul_f32 v[14:15], v[14:15], v[20:21] op_sel_hi:[0,1]
	v_pk_mul_f32 v[20:21], v[4:5], v[24:25]
	v_pk_mul_f32 v[16:17], v[6:7], v[16:17]
	v_pk_mul_f32 v[22:23], v[0:1], v[22:23]
	v_pk_mul_f32 v[24:25], v[2:3], v[14:15]
	v_cvt_pk_bf16_f32 v14, v20, v21
	v_cvt_pk_bf16_f32 v15, v16, v17
	v_cvt_pk_bf16_f32 v16, v22, v23
	v_cvt_pk_bf16_f32 v17, v24, v25
	global_store_dwordx4 v[18:19], v[14:17], off
	s_andn2_b64 exec, exec, s[0:1]
	s_cbranch_execnz .LBB0_335

; DI float logsigf(float x) { return fminf(x, 0.f) - __logf(1.f + __expf(-fabsf(x))); }
; DI void gla_item(const float* wgate, const float* bgate, const bf16_t* proj, bf16_t* mix, int item, LP unsigned char* lds3) {
;     ...
;     float cl[16]; float run = 0.f;
; #pragma unroll
;     for (int i = 0; i < 16; ++i) { const float* zp = zs + (tq * 16 + i) * 16; float x = bgv;
; #pragma unroll
;       for (int q = 0; q < 16; ++q) x += zp[q] * wg[q];
;       run += logsigf(x) * (1.f / 16.f); cl[i] = run; }
;     seg[tq * 128 + d] = run;
.LBB0_652:
	ds_read_b128 v[228:231], v106
	ds_read_b128 v[232:235], v106 offset:16
	ds_read_b128 v[236:239], v106 offset:32
	ds_read_b128 v[240:243], v106 offset:48
	ds_read_b128 v[244:247], v106 offset:64
	ds_read_b128 v[248:251], v106 offset:80
	s_mov_b32 s2, 0x3d800000
	s_waitcnt lgkmcnt(5)
	v_fma_f32 v32, v85, v228, v97
	v_fmac_f32_e32 v32, v57, v229
	v_fmac_f32_e32 v32, v67, v230
	v_fmac_f32_e32 v32, v71, v231
	ds_read_b128 v[228:231], v106 offset:96
	s_waitcnt lgkmcnt(5)
	v_fmac_f32_e32 v32, v73, v232
	v_fmac_f32_e32 v32, v75, v233
	v_fmac_f32_e32 v32, v77, v234
	v_fmac_f32_e32 v32, v79, v235
	ds_read_b128 v[232:235], v106 offset:112
	s_waitcnt lgkmcnt(5)
	v_fmac_f32_e32 v32, v81, v236
	v_fmac_f32_e32 v32, v83, v237
	v_fmac_f32_e32 v32, v87, v238
	v_fmac_f32_e32 v32, v89, v239
	ds_read_b128 v[236:239], v106 offset:128
	s_waitcnt lgkmcnt(5)
	v_fmac_f32_e32 v32, v91, v240
	v_fmac_f32_e32 v32, v93, v241
	v_fmac_f32_e32 v32, v95, v242
	v_fmac_f32_e32 v32, v99, v243
	ds_read_b128 v[240:243], v106 offset:144
	v_min_f32_e32 v33, 0, v32
	v_mul_f32_e64 v32, |v32|, s33
	v_exp_f32_e32 v32, v32
	v_lshlrev_b32_e32 v211, 16, v211
	v_mul_f32_e32 v211, 0x3db504f3, v211
	v_add_f32_e32 v32, 1.0, v32
	v_cmp_gt_f32_e32 vcc, s92, v32
	v_lshlrev_b32_e32 v210, 16, v210
	v_lshlrev_b32_e32 v208, 16, v208
	v_cndmask_b32_e64 v34, 0, 32, vcc
	v_ldexp_f32 v32, v32, v34
	v_log_f32_e32 v32, v32
	s_nop 0
	v_mul_f32_e32 v34, 0x3f317217, v32
	v_fma_f32 v34, v32, s93, -v34
	v_fmac_f32_e32 v34, 0x3377d1cf, v32
	v_fmac_f32_e32 v34, 0x3f317217, v32
	v_cmp_lt_f32_e64 s[52:53], |v32|, s96
	s_nop 1
	v_cndmask_b32_e64 v32, v32, v34, s[52:53]
	v_cndmask_b32_e32 v34, 0, v200, vcc
	v_sub_f32_e32 v32, v32, v34
	v_sub_f32_e32 v32, v33, v32
	s_waitcnt lgkmcnt(5)
	v_fma_f32 v33, v85, v244, v97
	v_fmac_f32_e32 v33, v57, v245
	v_fmac_f32_e32 v33, v67, v246
	v_fmac_f32_e32 v33, v71, v247
	ds_read_b128 v[244:247], v106 offset:160
	v_fma_f32 v32, v32, s2, 0
	s_waitcnt lgkmcnt(5)
	v_fmac_f32_e32 v33, v73, v248
	v_fmac_f32_e32 v33, v75, v249
	v_fmac_f32_e32 v33, v77, v250
	v_fmac_f32_e32 v33, v79, v251
	ds_read_b128 v[248:251], v106 offset:176
	s_waitcnt lgkmcnt(5)
	v_fmac_f32_e32 v33, v81, v228
	v_fmac_f32_e32 v33, v83, v229
	v_fmac_f32_e32 v33, v87, v230
	v_fmac_f32_e32 v33, v89, v231
	ds_read_b128 v[228:231], v106 offset:192
	s_waitcnt lgkmcnt(5)
	v_fmac_f32_e32 v33, v91, v232
	v_fmac_f32_e32 v33, v93, v233
	v_fmac_f32_e32 v33, v95, v234
	v_fmac_f32_e32 v33, v99, v235
	ds_read_b128 v[232:235], v106 offset:208
	v_min_f32_e32 v34, 0, v33
	v_mul_f32_e64 v33, |v33|, s33
	v_exp_f32_e32 v33, v33
	s_nop 0
	v_add_f32_e32 v33, 1.0, v33
	v_cmp_gt_f32_e32 vcc, s92, v33
	s_nop 1
	v_cndmask_b32_e64 v35, 0, 32, vcc
	v_ldexp_f32 v33, v33, v35
	v_log_f32_e32 v33, v33
	s_nop 0
	v_mul_f32_e32 v35, 0x3f317217, v33
	v_fma_f32 v35, v33, s93, -v35
	v_fmac_f32_e32 v35, 0x3377d1cf, v33
	v_fmac_f32_e32 v35, 0x3f317217, v33
	v_cmp_lt_f32_e64 s[52:53], |v33|, s96
	s_nop 1
	v_cndmask_b32_e64 v33, v33, v35, s[52:53]
	v_cndmask_b32_e32 v35, 0, v200, vcc
	v_sub_f32_e32 v33, v33, v35
	v_sub_f32_e32 v33, v34, v33
	s_waitcnt lgkmcnt(5)
	v_fma_f32 v34, v85, v236, v97
	v_fmac_f32_e32 v34, v57, v237
	v_fmac_f32_e32 v34, v67, v238
	v_fmac_f32_e32 v34, v71, v239
	ds_read_b128 v[236:239], v106 offset:224
	v_fmamk_f32 v33, v33, 0x3d800000, v32
	s_waitcnt lgkmcnt(5)
	v_fmac_f32_e32 v34, v73, v240
	v_fmac_f32_e32 v34, v75, v241
	v_fmac_f32_e32 v34, v77, v242
	v_fmac_f32_e32 v34, v79, v243
	ds_read_b128 v[240:243], v106 offset:240
	s_waitcnt lgkmcnt(5)
	v_fmac_f32_e32 v34, v81, v244
	v_fmac_f32_e32 v34, v83, v245
	v_fmac_f32_e32 v34, v87, v246
	v_fmac_f32_e32 v34, v89, v247
	ds_read_b128 v[244:247], v106 offset:256
	s_waitcnt lgkmcnt(5)
	v_fmac_f32_e32 v34, v91, v248
	v_fmac_f32_e32 v34, v93, v249
	v_fmac_f32_e32 v34, v95, v250
	v_fmac_f32_e32 v34, v99, v251
	ds_read_b128 v[248:251], v106 offset:272
	v_min_f32_e32 v35, 0, v34
	v_mul_f32_e64 v34, |v34|, s33
	v_exp_f32_e32 v34, v34
	s_nop 0
	v_add_f32_e32 v34, 1.0, v34
	v_cmp_gt_f32_e32 vcc, s92, v34
	s_nop 1
	v_cndmask_b32_e64 v212, 0, 32, vcc
	v_ldexp_f32 v34, v34, v212
	v_log_f32_e32 v34, v34
	s_nop 0
	v_mul_f32_e32 v212, 0x3f317217, v34
	v_fma_f32 v212, v34, s93, -v212
	v_fmac_f32_e32 v212, 0x3377d1cf, v34
	v_fmac_f32_e32 v212, 0x3f317217, v34
	v_cmp_lt_f32_e64 s[52:53], |v34|, s96
	s_nop 1
	v_cndmask_b32_e64 v34, v34, v212, s[52:53]
	v_cndmask_b32_e32 v212, 0, v200, vcc
	v_sub_f32_e32 v34, v34, v212
	v_sub_f32_e32 v34, v35, v34
	v_fmamk_f32 v34, v34, 0x3d800000, v33
	s_waitcnt lgkmcnt(5)
	v_fma_f32 v35, v85, v228, v97
	v_fmac_f32_e32 v35, v57, v229
	v_fmac_f32_e32 v35, v67, v230
	v_fmac_f32_e32 v35, v71, v231
	ds_read_b128 v[228:231], v106 offset:288
	s_waitcnt lgkmcnt(5)
	v_fmac_f32_e32 v35, v73, v232
	v_fmac_f32_e32 v35, v75, v233
	v_fmac_f32_e32 v35, v77, v234
	v_fmac_f32_e32 v35, v79, v235
	ds_read_b128 v[232:235], v106 offset:304
	s_waitcnt lgkmcnt(5)
	v_fmac_f32_e32 v35, v81, v236
	v_fmac_f32_e32 v35, v83, v237
	v_fmac_f32_e32 v35, v87, v238
	v_fmac_f32_e32 v35, v89, v239
	ds_read_b128 v[236:239], v106 offset:320
	s_waitcnt lgkmcnt(5)
	v_fmac_f32_e32 v35, v91, v240
	v_fmac_f32_e32 v35, v93, v241
	v_fmac_f32_e32 v35, v95, v242
	v_fmac_f32_e32 v35, v99, v243
	ds_read_b128 v[240:243], v106 offset:336
	v_min_f32_e32 v212, 0, v35
	v_mul_f32_e64 v35, |v35|, s33
	v_exp_f32_e32 v35, v35
	s_nop 0
	v_add_f32_e32 v35, 1.0, v35
	v_cmp_gt_f32_e32 vcc, s92, v35
	s_nop 1
	v_cndmask_b32_e64 v213, 0, 32, vcc
	v_ldexp_f32 v35, v35, v213
	v_log_f32_e32 v35, v35
	s_nop 0
	v_mul_f32_e32 v213, 0x3f317217, v35
	v_fma_f32 v213, v35, s93, -v213
	v_fmac_f32_e32 v213, 0x3377d1cf, v35
	v_fmac_f32_e32 v213, 0x3f317217, v35
	v_cmp_lt_f32_e64 s[52:53], |v35|, s96
	s_nop 1
	v_cndmask_b32_e64 v35, v35, v213, s[52:53]
	v_cndmask_b32_e32 v213, 0, v200, vcc
	v_sub_f32_e32 v35, v35, v213
	v_sub_f32_e32 v35, v212, v35
	v_fmamk_f32 v35, v35, 0x3d800000, v34
	s_waitcnt lgkmcnt(5)
; DI float logsigf(float x) { return fminf(x, 0.f) - __logf(1.f + __expf(-fabsf(x))); }
; DI void gla_item(const float* wgate, const float* bgate, const bf16_t* proj, bf16_t* mix, int item, LP unsigned char* lds3) {
;     ...
;     float cl[16]; float run = 0.f;
; #pragma unroll
;     for (int i = 0; i < 16; ++i) { const float* zp = zs + (tq * 16 + i) * 16; float x = bgv;
; #pragma unroll
;       for (int q = 0; q < 16; ++q) x += zp[q] * wg[q];
;       run += logsigf(x) * (1.f / 16.f); cl[i] = run; }
;     seg[tq * 128 + d] = run;
	v_fma_f32 v216, v85, v244, v97
	v_fmac_f32_e32 v216, v57, v245
	v_fmac_f32_e32 v216, v67, v246
	v_fmac_f32_e32 v216, v71, v247
	ds_read_b128 v[244:247], v106 offset:352
	s_waitcnt lgkmcnt(5)
	v_fmac_f32_e32 v216, v73, v248
	v_fmac_f32_e32 v216, v75, v249
	v_fmac_f32_e32 v216, v77, v250
	v_fmac_f32_e32 v216, v79, v251
	ds_read_b128 v[248:251], v106 offset:368
	s_waitcnt lgkmcnt(5)
	v_fmac_f32_e32 v216, v81, v228
	v_fmac_f32_e32 v216, v83, v229
	v_fmac_f32_e32 v216, v87, v230
	v_fmac_f32_e32 v216, v89, v231
	ds_read_b128 v[228:231], v106 offset:384
	s_waitcnt lgkmcnt(5)
	v_fmac_f32_e32 v216, v91, v232
	v_fmac_f32_e32 v216, v93, v233
	v_fmac_f32_e32 v216, v95, v234
	v_fmac_f32_e32 v216, v99, v235
	ds_read_b128 v[232:235], v106 offset:400
	v_mul_f32_e64 v213, |v216|, s33
	v_exp_f32_e32 v213, v213
	v_min_f32_e32 v212, 0, v216
	v_add_f32_e32 v213, 1.0, v213
	v_cmp_gt_f32_e32 vcc, s92, v213
	s_nop 1
	v_cndmask_b32_e64 v214, 0, 32, vcc
	v_ldexp_f32 v213, v213, v214
	v_log_f32_e32 v213, v213
	s_nop 0
	v_mul_f32_e32 v214, 0x3f317217, v213
	v_fma_f32 v214, v213, s93, -v214
	v_fmac_f32_e32 v214, 0x3377d1cf, v213
	v_fmac_f32_e32 v214, 0x3f317217, v213
	v_cmp_lt_f32_e64 s[52:53], |v213|, s96
	s_nop 1
	v_cndmask_b32_e64 v213, v213, v214, s[52:53]
	v_cndmask_b32_e32 v214, 0, v200, vcc
	v_sub_f32_e32 v213, v213, v214
	v_sub_f32_e32 v212, v212, v213
	v_fmamk_f32 v212, v212, 0x3d800000, v35
	s_waitcnt lgkmcnt(5)
	v_fma_f32 v213, v85, v236, v97
	v_fmac_f32_e32 v213, v57, v237
	v_fmac_f32_e32 v213, v67, v238
	v_fmac_f32_e32 v213, v71, v239
	ds_read_b128 v[236:239], v106 offset:416
	s_waitcnt lgkmcnt(5)
	v_fmac_f32_e32 v213, v73, v240
	v_fmac_f32_e32 v213, v75, v241
	v_fmac_f32_e32 v213, v77, v242
	v_fmac_f32_e32 v213, v79, v243
	ds_read_b128 v[240:243], v106 offset:432
	s_waitcnt lgkmcnt(5)
	v_fmac_f32_e32 v213, v81, v244
	v_fmac_f32_e32 v213, v83, v245
	v_fmac_f32_e32 v213, v87, v246
	v_fmac_f32_e32 v213, v89, v247
	ds_read_b128 v[244:247], v106 offset:448
	s_waitcnt lgkmcnt(5)
	v_fmac_f32_e32 v213, v91, v248
	v_fmac_f32_e32 v213, v93, v249
	v_fmac_f32_e32 v213, v95, v250
	v_fmac_f32_e32 v213, v99, v251
	ds_read_b128 v[248:251], v106 offset:464
	v_min_f32_e32 v214, 0, v213
	v_mul_f32_e64 v213, |v213|, s33
	v_exp_f32_e32 v213, v213
	s_nop 0
	v_add_f32_e32 v213, 1.0, v213
	v_cmp_gt_f32_e32 vcc, s92, v213
	s_nop 1
	v_cndmask_b32_e64 v215, 0, 32, vcc
	v_ldexp_f32 v213, v213, v215
	v_log_f32_e32 v213, v213
	s_nop 0
	v_mul_f32_e32 v215, 0x3f317217, v213
	v_fma_f32 v215, v213, s93, -v215
	v_fmac_f32_e32 v215, 0x3377d1cf, v213
	v_fmac_f32_e32 v215, 0x3f317217, v213
	v_cmp_lt_f32_e64 s[52:53], |v213|, s96
	s_nop 1
	v_cndmask_b32_e64 v213, v213, v215, s[52:53]
	v_cndmask_b32_e32 v215, 0, v200, vcc
	v_sub_f32_e32 v213, v213, v215
	v_sub_f32_e32 v213, v214, v213
	v_fmamk_f32 v213, v213, 0x3d800000, v212
	s_waitcnt lgkmcnt(5)
	v_fma_f32 v218, v85, v228, v97
	v_fmac_f32_e32 v218, v57, v229
	v_fmac_f32_e32 v218, v67, v230
	v_fmac_f32_e32 v218, v71, v231
	ds_read_b128 v[228:231], v106 offset:480
	s_waitcnt lgkmcnt(5)
	v_fmac_f32_e32 v218, v73, v232
	v_fmac_f32_e32 v218, v75, v233
	v_fmac_f32_e32 v218, v77, v234
	v_fmac_f32_e32 v218, v79, v235
	ds_read_b128 v[232:235], v106 offset:496
	s_waitcnt lgkmcnt(5)
	v_fmac_f32_e32 v218, v81, v236
	v_fmac_f32_e32 v218, v83, v237
	v_fmac_f32_e32 v218, v87, v238
	v_fmac_f32_e32 v218, v89, v239
	ds_read_b128 v[236:239], v106 offset:512
	s_waitcnt lgkmcnt(5)
	v_fmac_f32_e32 v218, v91, v240
	v_fmac_f32_e32 v218, v93, v241
	v_fmac_f32_e32 v218, v95, v242
	v_fmac_f32_e32 v218, v99, v243
	ds_read_b128 v[240:243], v106 offset:528
	v_mul_f32_e64 v215, |v218|, s33
	v_exp_f32_e32 v215, v215
	v_min_f32_e32 v214, 0, v218
	v_add_f32_e32 v215, 1.0, v215
	v_cmp_gt_f32_e32 vcc, s92, v215
	s_nop 1
	v_cndmask_b32_e64 v216, 0, 32, vcc
	v_ldexp_f32 v215, v215, v216
	v_log_f32_e32 v215, v215
	s_nop 0
	v_mul_f32_e32 v216, 0x3f317217, v215
	v_fma_f32 v216, v215, s93, -v216
	v_fmac_f32_e32 v216, 0x3377d1cf, v215
	v_fmac_f32_e32 v216, 0x3f317217, v215
	v_cmp_lt_f32_e64 s[52:53], |v215|, s96
	s_nop 1
	v_cndmask_b32_e64 v215, v215, v216, s[52:53]
	v_cndmask_b32_e32 v216, 0, v200, vcc
	v_sub_f32_e32 v215, v215, v216
	v_sub_f32_e32 v214, v214, v215
	v_fmamk_f32 v214, v214, 0x3d800000, v213
	s_waitcnt lgkmcnt(5)
	v_fma_f32 v215, v85, v244, v97
	v_fmac_f32_e32 v215, v57, v245
	v_fmac_f32_e32 v215, v67, v246
	v_fmac_f32_e32 v215, v71, v247
	ds_read_b128 v[244:247], v106 offset:544
	s_waitcnt lgkmcnt(5)
	v_fmac_f32_e32 v215, v73, v248
	v_fmac_f32_e32 v215, v75, v249
	v_fmac_f32_e32 v215, v77, v250
	v_fmac_f32_e32 v215, v79, v251
	ds_read_b128 v[248:251], v106 offset:560
	s_waitcnt lgkmcnt(5)
	v_fmac_f32_e32 v215, v81, v228
	v_fmac_f32_e32 v215, v83, v229
	v_fmac_f32_e32 v215, v87, v230
	v_fmac_f32_e32 v215, v89, v231
	ds_read_b128 v[228:231], v106 offset:576
	s_waitcnt lgkmcnt(5)
	v_fmac_f32_e32 v215, v91, v232
	v_fmac_f32_e32 v215, v93, v233
	v_fmac_f32_e32 v215, v95, v234
	v_fmac_f32_e32 v215, v99, v235
	ds_read_b128 v[232:235], v106 offset:592
	v_min_f32_e32 v216, 0, v215
	v_mul_f32_e64 v215, |v215|, s33
	v_exp_f32_e32 v215, v215
	s_nop 0
	v_add_f32_e32 v215, 1.0, v215
	v_cmp_gt_f32_e32 vcc, s92, v215
	s_nop 1
	v_cndmask_b32_e64 v217, 0, 32, vcc
	v_ldexp_f32 v215, v215, v217
	v_log_f32_e32 v215, v215
	s_nop 0
	v_mul_f32_e32 v217, 0x3f317217, v215
	v_fma_f32 v217, v215, s93, -v217
	v_fmac_f32_e32 v217, 0x3377d1cf, v215
	v_fmac_f32_e32 v217, 0x3f317217, v215
	v_cmp_lt_f32_e64 s[52:53], |v215|, s96
	s_nop 1
	v_cndmask_b32_e64 v215, v215, v217, s[52:53]
	v_cndmask_b32_e32 v217, 0, v200, vcc
	v_sub_f32_e32 v215, v215, v217
	v_sub_f32_e32 v215, v216, v215
	v_fmamk_f32 v215, v215, 0x3d800000, v214
	s_waitcnt lgkmcnt(5)
; DI float logsigf(float x) { return fminf(x, 0.f) - __logf(1.f + __expf(-fabsf(x))); }
; DI void gla_item(const float* wgate, const float* bgate, const bf16_t* proj, bf16_t* mix, int item, LP unsigned char* lds3) {
;     ...
;     float cl[16]; float run = 0.f;
; #pragma unroll
;     for (int i = 0; i < 16; ++i) { const float* zp = zs + (tq * 16 + i) * 16; float x = bgv;
; #pragma unroll
;       for (int q = 0; q < 16; ++q) x += zp[q] * wg[q];
;       run += logsigf(x) * (1.f / 16.f); cl[i] = run; }
;     seg[tq * 128 + d] = run;
	v_fma_f32 v220, v85, v236, v97
	v_fmac_f32_e32 v220, v57, v237
	v_fmac_f32_e32 v220, v67, v238
	v_fmac_f32_e32 v220, v71, v239
	ds_read_b128 v[236:239], v106 offset:608
	s_waitcnt lgkmcnt(5)
	v_fmac_f32_e32 v220, v73, v240
	v_fmac_f32_e32 v220, v75, v241
	v_fmac_f32_e32 v220, v77, v242
	v_fmac_f32_e32 v220, v79, v243
	ds_read_b128 v[240:243], v106 offset:624
	s_waitcnt lgkmcnt(5)
	v_fmac_f32_e32 v220, v81, v244
	v_fmac_f32_e32 v220, v83, v245
	v_fmac_f32_e32 v220, v87, v246
	v_fmac_f32_e32 v220, v89, v247
	ds_read_b128 v[244:247], v106 offset:640
	s_waitcnt lgkmcnt(5)
	v_fmac_f32_e32 v220, v91, v248
	v_fmac_f32_e32 v220, v93, v249
	v_fmac_f32_e32 v220, v95, v250
	v_fmac_f32_e32 v220, v99, v251
	ds_read_b128 v[248:251], v106 offset:656
	v_mul_f32_e64 v217, |v220|, s33
	v_exp_f32_e32 v217, v217
	v_min_f32_e32 v216, 0, v220
	v_add_f32_e32 v217, 1.0, v217
	v_cmp_gt_f32_e32 vcc, s92, v217
	s_nop 1
	v_cndmask_b32_e64 v218, 0, 32, vcc
	v_ldexp_f32 v217, v217, v218
	v_log_f32_e32 v217, v217
	s_nop 0
	v_mul_f32_e32 v218, 0x3f317217, v217
	v_fma_f32 v218, v217, s93, -v218
	v_fmac_f32_e32 v218, 0x3377d1cf, v217
	v_fmac_f32_e32 v218, 0x3f317217, v217
	v_cmp_lt_f32_e64 s[52:53], |v217|, s96
	s_nop 1
	v_cndmask_b32_e64 v217, v217, v218, s[52:53]
	v_cndmask_b32_e32 v218, 0, v200, vcc
	v_sub_f32_e32 v217, v217, v218
	v_sub_f32_e32 v216, v216, v217
	v_fmamk_f32 v216, v216, 0x3d800000, v215
	s_waitcnt lgkmcnt(5)
	v_fma_f32 v217, v85, v228, v97
	v_fmac_f32_e32 v217, v57, v229
	v_fmac_f32_e32 v217, v67, v230
	v_fmac_f32_e32 v217, v71, v231
	ds_read_b128 v[228:231], v106 offset:672
	s_waitcnt lgkmcnt(5)
	v_fmac_f32_e32 v217, v73, v232
	v_fmac_f32_e32 v217, v75, v233
	v_fmac_f32_e32 v217, v77, v234
	v_fmac_f32_e32 v217, v79, v235
	ds_read_b128 v[232:235], v106 offset:688
	s_waitcnt lgkmcnt(5)
	v_fmac_f32_e32 v217, v81, v236
	v_fmac_f32_e32 v217, v83, v237
	v_fmac_f32_e32 v217, v87, v238
	v_fmac_f32_e32 v217, v89, v239
	ds_read_b128 v[236:239], v106 offset:704
	s_waitcnt lgkmcnt(5)
	v_fmac_f32_e32 v217, v91, v240
	v_fmac_f32_e32 v217, v93, v241
	v_fmac_f32_e32 v217, v95, v242
	v_fmac_f32_e32 v217, v99, v243
	ds_read_b128 v[240:243], v106 offset:720
	v_min_f32_e32 v218, 0, v217
	v_mul_f32_e64 v217, |v217|, s33
	v_exp_f32_e32 v217, v217
	s_nop 0
	v_add_f32_e32 v217, 1.0, v217
	v_cmp_gt_f32_e32 vcc, s92, v217
	s_nop 1
	v_cndmask_b32_e64 v219, 0, 32, vcc
	v_ldexp_f32 v217, v217, v219
	v_log_f32_e32 v217, v217
	s_nop 0
	v_mul_f32_e32 v219, 0x3f317217, v217
	v_fma_f32 v219, v217, s93, -v219
	v_fmac_f32_e32 v219, 0x3377d1cf, v217
	v_fmac_f32_e32 v219, 0x3f317217, v217
	v_cmp_lt_f32_e64 s[52:53], |v217|, s96
	s_nop 1
	v_cndmask_b32_e64 v217, v217, v219, s[52:53]
	v_cndmask_b32_e32 v219, 0, v200, vcc
	v_sub_f32_e32 v217, v217, v219
	v_sub_f32_e32 v217, v218, v217
	v_fmamk_f32 v217, v217, 0x3d800000, v216
	s_waitcnt lgkmcnt(5)
	v_fma_f32 v222, v85, v244, v97
	v_fmac_f32_e32 v222, v57, v245
	v_fmac_f32_e32 v222, v67, v246
	v_fmac_f32_e32 v222, v71, v247
	ds_read_b128 v[244:247], v106 offset:736
	s_waitcnt lgkmcnt(5)
	v_fmac_f32_e32 v222, v73, v248
	v_fmac_f32_e32 v222, v75, v249
	v_fmac_f32_e32 v222, v77, v250
	v_fmac_f32_e32 v222, v79, v251
	ds_read_b128 v[248:251], v106 offset:752
	s_waitcnt lgkmcnt(5)
	v_fmac_f32_e32 v222, v81, v228
	v_fmac_f32_e32 v222, v83, v229
	v_fmac_f32_e32 v222, v87, v230
	v_fmac_f32_e32 v222, v89, v231
	ds_read_b128 v[228:231], v106 offset:768
	s_waitcnt lgkmcnt(5)
	v_fmac_f32_e32 v222, v91, v232
	v_fmac_f32_e32 v222, v93, v233
	v_fmac_f32_e32 v222, v95, v234
	v_fmac_f32_e32 v222, v99, v235
	ds_read_b128 v[232:235], v106 offset:784
	v_mul_f32_e64 v219, |v222|, s33
	v_exp_f32_e32 v219, v219
	v_min_f32_e32 v218, 0, v222
	v_add_f32_e32 v219, 1.0, v219
	v_cmp_gt_f32_e32 vcc, s92, v219
	s_nop 1
	v_cndmask_b32_e64 v220, 0, 32, vcc
	v_ldexp_f32 v219, v219, v220
	v_log_f32_e32 v219, v219
	s_nop 0
	v_mul_f32_e32 v220, 0x3f317217, v219
	v_fma_f32 v220, v219, s93, -v220
	v_fmac_f32_e32 v220, 0x3377d1cf, v219
	v_fmac_f32_e32 v220, 0x3f317217, v219
	v_cmp_lt_f32_e64 s[52:53], |v219|, s96
	s_nop 1
	v_cndmask_b32_e64 v219, v219, v220, s[52:53]
	v_cndmask_b32_e32 v220, 0, v200, vcc
	v_sub_f32_e32 v219, v219, v220
	v_sub_f32_e32 v218, v218, v219
	v_fmamk_f32 v218, v218, 0x3d800000, v217
	s_waitcnt lgkmcnt(5)
	v_fma_f32 v219, v85, v236, v97
	v_fmac_f32_e32 v219, v57, v237
	v_fmac_f32_e32 v219, v67, v238
	v_fmac_f32_e32 v219, v71, v239
	ds_read_b128 v[236:239], v106 offset:800
	s_waitcnt lgkmcnt(5)
	v_fmac_f32_e32 v219, v73, v240
	v_fmac_f32_e32 v219, v75, v241
	v_fmac_f32_e32 v219, v77, v242
	v_fmac_f32_e32 v219, v79, v243
	ds_read_b128 v[240:243], v106 offset:816
	s_waitcnt lgkmcnt(5)
	v_fmac_f32_e32 v219, v81, v244
	v_fmac_f32_e32 v219, v83, v245
	v_fmac_f32_e32 v219, v87, v246
	v_fmac_f32_e32 v219, v89, v247
	ds_read_b128 v[244:247], v106 offset:832
	s_waitcnt lgkmcnt(5)
	v_fmac_f32_e32 v219, v91, v248
	v_fmac_f32_e32 v219, v93, v249
	v_fmac_f32_e32 v219, v95, v250
	v_fmac_f32_e32 v219, v99, v251
	ds_read_b128 v[248:251], v106 offset:848
	v_min_f32_e32 v220, 0, v219
	v_mul_f32_e64 v219, |v219|, s33
	v_exp_f32_e32 v219, v219
	s_nop 0
	v_add_f32_e32 v219, 1.0, v219
	v_cmp_gt_f32_e32 vcc, s92, v219
	s_nop 1
	v_cndmask_b32_e64 v221, 0, 32, vcc
	v_ldexp_f32 v219, v219, v221
	v_log_f32_e32 v219, v219
	s_nop 0
	v_mul_f32_e32 v221, 0x3f317217, v219
	v_fma_f32 v221, v219, s93, -v221
	v_fmac_f32_e32 v221, 0x3377d1cf, v219
	v_fmac_f32_e32 v221, 0x3f317217, v219
	v_cmp_lt_f32_e64 s[52:53], |v219|, s96
	s_nop 1
	v_cndmask_b32_e64 v219, v219, v221, s[52:53]
	v_cndmask_b32_e32 v221, 0, v200, vcc
	v_sub_f32_e32 v219, v219, v221
	v_sub_f32_e32 v219, v220, v219
	v_fmamk_f32 v219, v219, 0x3d800000, v218
	s_waitcnt lgkmcnt(5)
; DI float logsigf(float x) { return fminf(x, 0.f) - __logf(1.f + __expf(-fabsf(x))); }
; DI void gla_item(const float* wgate, const float* bgate, const bf16_t* proj, bf16_t* mix, int item, LP unsigned char* lds3) {
;     ...
;     float cl[16]; float run = 0.f;
; #pragma unroll
;     for (int i = 0; i < 16; ++i) { const float* zp = zs + (tq * 16 + i) * 16; float x = bgv;
; #pragma unroll
;       for (int q = 0; q < 16; ++q) x += zp[q] * wg[q];
;       run += logsigf(x) * (1.f / 16.f); cl[i] = run; }
;     seg[tq * 128 + d] = run;
;     __syncthreads();
	v_fma_f32 v224, v85, v228, v97
	v_fmac_f32_e32 v224, v57, v229
	v_fmac_f32_e32 v224, v67, v230
	v_fmac_f32_e32 v224, v71, v231
	ds_read_b128 v[228:231], v106 offset:864
	s_waitcnt lgkmcnt(5)
	v_fmac_f32_e32 v224, v73, v232
	v_fmac_f32_e32 v224, v75, v233
	v_fmac_f32_e32 v224, v77, v234
	v_fmac_f32_e32 v224, v79, v235
	ds_read_b128 v[232:235], v106 offset:880
	s_waitcnt lgkmcnt(5)
	v_fmac_f32_e32 v224, v81, v236
	v_fmac_f32_e32 v224, v83, v237
	v_fmac_f32_e32 v224, v87, v238
	v_fmac_f32_e32 v224, v89, v239
	ds_read_b128 v[236:239], v106 offset:896
	s_waitcnt lgkmcnt(5)
	v_fmac_f32_e32 v224, v91, v240
	v_fmac_f32_e32 v224, v93, v241
	v_fmac_f32_e32 v224, v95, v242
	v_fmac_f32_e32 v224, v99, v243
	ds_read_b128 v[240:243], v106 offset:912
	v_mul_f32_e64 v221, |v224|, s33
	v_exp_f32_e32 v221, v221
	v_min_f32_e32 v220, 0, v224
	v_add_f32_e32 v221, 1.0, v221
	v_cmp_gt_f32_e32 vcc, s92, v221
	s_nop 1
	v_cndmask_b32_e64 v222, 0, 32, vcc
	v_ldexp_f32 v221, v221, v222
	v_log_f32_e32 v221, v221
	s_nop 0
	v_mul_f32_e32 v222, 0x3f317217, v221
	v_fma_f32 v222, v221, s93, -v222
	v_fmac_f32_e32 v222, 0x3377d1cf, v221
	v_fmac_f32_e32 v222, 0x3f317217, v221
	v_cmp_lt_f32_e64 s[52:53], |v221|, s96
	s_nop 1
	v_cndmask_b32_e64 v221, v221, v222, s[52:53]
	v_cndmask_b32_e32 v222, 0, v200, vcc
	v_sub_f32_e32 v221, v221, v222
	v_sub_f32_e32 v220, v220, v221
	v_fmamk_f32 v220, v220, 0x3d800000, v219
	s_waitcnt lgkmcnt(5)
	v_fma_f32 v221, v85, v244, v97
	v_fmac_f32_e32 v221, v57, v245
	v_fmac_f32_e32 v221, v67, v246
	v_fmac_f32_e32 v221, v71, v247
	ds_read_b128 v[244:247], v106 offset:928
	s_waitcnt lgkmcnt(5)
	v_fmac_f32_e32 v221, v73, v248
	v_fmac_f32_e32 v221, v75, v249
	v_fmac_f32_e32 v221, v77, v250
	v_fmac_f32_e32 v221, v79, v251
	ds_read_b128 v[248:251], v106 offset:944
	s_waitcnt lgkmcnt(5)
	v_fmac_f32_e32 v221, v81, v228
	v_fmac_f32_e32 v221, v83, v229
	v_fmac_f32_e32 v221, v87, v230
	v_fmac_f32_e32 v221, v89, v231
	ds_read_b128 v[228:231], v106 offset:960
	s_waitcnt lgkmcnt(5)
	v_fmac_f32_e32 v221, v91, v232
	v_fmac_f32_e32 v221, v93, v233
	v_fmac_f32_e32 v221, v95, v234
	v_fmac_f32_e32 v221, v99, v235
	ds_read_b128 v[232:235], v106 offset:976
	v_min_f32_e32 v222, 0, v221
	v_mul_f32_e64 v221, |v221|, s33
	v_exp_f32_e32 v221, v221
	s_nop 0
	v_add_f32_e32 v221, 1.0, v221
	v_cmp_gt_f32_e32 vcc, s92, v221
	s_nop 1
	v_cndmask_b32_e64 v223, 0, 32, vcc
	v_ldexp_f32 v221, v221, v223
	v_log_f32_e32 v221, v221
	s_nop 0
	v_mul_f32_e32 v223, 0x3f317217, v221
	v_fma_f32 v223, v221, s93, -v223
	v_fmac_f32_e32 v223, 0x3377d1cf, v221
	v_fmac_f32_e32 v223, 0x3f317217, v221
	v_cmp_lt_f32_e64 s[52:53], |v221|, s96
	s_nop 1
	v_cndmask_b32_e64 v221, v221, v223, s[52:53]
	v_cndmask_b32_e32 v223, 0, v200, vcc
	v_sub_f32_e32 v221, v221, v223
	v_sub_f32_e32 v221, v222, v221
	v_fmamk_f32 v221, v221, 0x3d800000, v220
	s_waitcnt lgkmcnt(5)
	v_fma_f32 v226, v85, v236, v97
	v_fmac_f32_e32 v226, v57, v237
	v_fmac_f32_e32 v226, v67, v238
	v_fmac_f32_e32 v226, v71, v239
	ds_read_b128 v[236:239], v106 offset:992
	s_waitcnt lgkmcnt(5)
	v_fmac_f32_e32 v226, v73, v240
	v_fmac_f32_e32 v226, v75, v241
	v_fmac_f32_e32 v226, v77, v242
	v_fmac_f32_e32 v226, v79, v243
	ds_read_b128 v[240:243], v106 offset:1008
	s_waitcnt lgkmcnt(5)
	v_fmac_f32_e32 v226, v81, v244
	v_fmac_f32_e32 v226, v83, v245
	v_fmac_f32_e32 v226, v87, v246
	v_fmac_f32_e32 v226, v89, v247
	s_waitcnt lgkmcnt(4)
	v_fmac_f32_e32 v226, v91, v248
	v_fmac_f32_e32 v226, v93, v249
	v_fmac_f32_e32 v226, v95, v250
	v_fmac_f32_e32 v226, v99, v251
	v_mul_f32_e64 v223, |v226|, s33
	v_exp_f32_e32 v223, v223
	v_min_f32_e32 v222, 0, v226
	v_add_f32_e32 v223, 1.0, v223
	v_cmp_gt_f32_e32 vcc, s92, v223
	s_nop 1
	v_cndmask_b32_e64 v224, 0, 32, vcc
	v_ldexp_f32 v223, v223, v224
	v_log_f32_e32 v223, v223
	s_nop 0
	v_mul_f32_e32 v224, 0x3f317217, v223
	v_fma_f32 v224, v223, s93, -v224
	v_fmac_f32_e32 v224, 0x3377d1cf, v223
	v_fmac_f32_e32 v224, 0x3f317217, v223
	v_cmp_lt_f32_e64 s[52:53], |v223|, s96
	s_nop 1
	v_cndmask_b32_e64 v223, v223, v224, s[52:53]
	v_cndmask_b32_e32 v224, 0, v200, vcc
	v_sub_f32_e32 v223, v223, v224
	v_sub_f32_e32 v222, v222, v223
	v_fmamk_f32 v222, v222, 0x3d800000, v221
	s_waitcnt lgkmcnt(3)
	v_fma_f32 v223, v85, v228, v97
	v_fmac_f32_e32 v223, v57, v229
	v_fmac_f32_e32 v223, v67, v230
	v_fmac_f32_e32 v223, v71, v231
	s_waitcnt lgkmcnt(2)
	v_fmac_f32_e32 v223, v73, v232
	v_fmac_f32_e32 v223, v75, v233
	v_fmac_f32_e32 v223, v77, v234
	v_fmac_f32_e32 v223, v79, v235
	s_waitcnt lgkmcnt(1)
	v_fmac_f32_e32 v223, v81, v236
	v_fmac_f32_e32 v223, v83, v237
	v_fmac_f32_e32 v223, v87, v238
	v_fmac_f32_e32 v223, v89, v239
	s_waitcnt lgkmcnt(0)
	v_fmac_f32_e32 v223, v91, v240
	v_fmac_f32_e32 v223, v93, v241
	v_fmac_f32_e32 v223, v95, v242
	v_fmac_f32_e32 v223, v99, v243
	v_min_f32_e32 v224, 0, v223
	v_mul_f32_e64 v223, |v223|, s33
	v_exp_f32_e32 v223, v223
	s_nop 0
	v_add_f32_e32 v223, 1.0, v223
	v_cmp_gt_f32_e32 vcc, s92, v223
	s_nop 1
	v_cndmask_b32_e64 v225, 0, 32, vcc
	v_ldexp_f32 v223, v223, v225
	v_log_f32_e32 v223, v223
	s_nop 0
	v_mul_f32_e32 v225, 0x3f317217, v223
	v_fma_f32 v225, v223, s93, -v225
	v_fmac_f32_e32 v225, 0x3377d1cf, v223
	v_fmac_f32_e32 v225, 0x3f317217, v223
	v_cmp_lt_f32_e64 s[52:53], |v223|, s96
	s_nop 1
	v_cndmask_b32_e64 v223, v223, v225, s[52:53]
	v_cndmask_b32_e32 v225, 0, v200, vcc
	v_sub_f32_e32 v223, v223, v225
	v_sub_f32_e32 v223, v224, v223
	v_fmamk_f32 v224, v223, 0x3d800000, v222
	ds_write_b32 v107, v224 offset:4096
	s_waitcnt lgkmcnt(0)
	s_barrier
; DI float bf2f(bf16_t b) { return __uint_as_float(((unsigned)b) << 16); }
; DI void gla_item(const float* wgate, const float* bgate, const bf16_t* proj, bf16_t* mix, int item, LP unsigned char* lds3) {
;     ...
;     float pre = 0.f, tot = 0.f;
; #pragma unroll
;     for (int q = 0; q < 4; ++q) { const float sv = seg[q * 128 + d]; tot += sv; if (q < tq) pre += sv; }
; #pragma unroll
;     for (int i = 0; i < 16; ++i) { const int t = tq * 16 + i; const float cum = pre + cl[i]; const float qf = bf2f(qv[i]), kf = bf2f(kv[i]);
;       Qd[t * 136 + d] = f2bf(qf * 0.08838834764831845f * __expf(cum));
;       Kd[t * 136 + d] = f2bf(kf * __expf(-cum));
;       KeT[d * 72 + t] = f2bf(kf * __expf(tot - cum)); }
	ds_read2st64_b32 v[226:227], v108 offset0:16 offset1:18
	s_waitcnt lgkmcnt(0)
	v_add_f32_e32 v223, 0, v226
	v_cndmask_b32_e64 v225, 0, v223, s[10:11]
	v_add_f32_e32 v226, v227, v225
	v_add_f32_e32 v223, v223, v227
	v_cndmask_b32_e64 v225, v225, v226, s[12:13]
	ds_read2st64_b32 v[226:227], v108 offset0:20 offset1:22
	s_waitcnt lgkmcnt(0)
	v_add_f32_e32 v223, v223, v226
	v_add_f32_e32 v226, v226, v225
	v_cndmask_b32_e64 v225, v225, v226, s[14:15]
	v_add_f32_e32 v226, v227, v225
	v_cndmask_b32_e64 v225, v225, v226, s[16:17]
	v_add_f32_e32 v32, v32, v225
	v_mul_f32_e32 v226, 0x3fb8aa3b, v32
	v_exp_f32_e32 v226, v226
	v_add_f32_e32 v223, v223, v227
	v_mul_f32_e32 v211, v211, v226
	v_cvt_pk_bf16_f32 v211, v211, s0
	ds_write_b16 v117, v211 offset:8192
	v_mul_f32_e32 v211, 0xbfb8aa3b, v32
	v_sub_f32_e32 v32, v223, v32
	v_mul_f32_e32 v32, 0x3fb8aa3b, v32
	v_exp_f32_e32 v211, v211
	v_exp_f32_e32 v32, v32
	v_mul_f32_e32 v211, v211, v210
	v_mul_f32_e32 v32, v32, v210
	v_cvt_pk_bf16_f32 v211, v211, s0
	v_cvt_pk_bf16_f32 v32, v32, s0
	ds_write_b16 v117, v211 offset:25600
	ds_write_b16 v118, v32 offset:43008
	v_add_f32_e32 v32, v33, v225
	v_lshlrev_b32_e32 v33, 16, v209
	v_mul_f32_e32 v209, 0x3fb8aa3b, v32
	v_exp_f32_e32 v209, v209
	v_mul_f32_e32 v33, 0x3db504f3, v33
	v_mul_f32_e32 v33, v33, v209
	v_cvt_pk_bf16_f32 v33, v33, s0
	ds_write_b16 v119, v33 offset:8192
	v_mul_f32_e32 v33, 0xbfb8aa3b, v32
	v_sub_f32_e32 v32, v223, v32
	v_mul_f32_e32 v32, 0x3fb8aa3b, v32
	v_exp_f32_e32 v33, v33
	v_exp_f32_e32 v32, v32
	v_mul_f32_e32 v33, v33, v208
	v_mul_f32_e32 v32, v32, v208
	v_cvt_pk_bf16_f32 v33, v33, s0
	v_cvt_pk_bf16_f32 v32, v32, s0
	ds_write_b16 v119, v33 offset:25600
	ds_write_b16 v118, v32 offset:43010
	v_add_f32_e32 v32, v34, v225
	v_lshlrev_b32_e32 v33, 16, v206
	v_mul_f32_e32 v206, 0x3fb8aa3b, v32
	v_exp_f32_e32 v206, v206
	v_mul_f32_e32 v33, 0x3db504f3, v33
	v_lshlrev_b32_e32 v34, 16, v207
	v_mul_f32_e32 v33, v33, v206
	v_cvt_pk_bf16_f32 v33, v33, s0
	ds_write_b16 v120, v33 offset:8192
	v_mul_f32_e32 v33, 0xbfb8aa3b, v32
	v_sub_f32_e32 v32, v223, v32
	v_mul_f32_e32 v32, 0x3fb8aa3b, v32
	v_exp_f32_e32 v33, v33
	v_exp_f32_e32 v32, v32
	v_mul_f32_e32 v33, v33, v34
	v_mul_f32_e32 v32, v32, v34
	v_cvt_pk_bf16_f32 v33, v33, s0
	v_cvt_pk_bf16_f32 v32, v32, s0
	ds_write_b16 v120, v33 offset:25600
	ds_write_b16 v118, v32 offset:43012
	v_add_f32_e32 v32, v35, v225
	v_mul_f32_e32 v35, 0x3fb8aa3b, v32
	v_exp_f32_e32 v35, v35
	v_lshlrev_b32_e32 v33, 16, v205
	v_mul_f32_e32 v33, 0x3db504f3, v33
	v_lshlrev_b32_e32 v34, 16, v204
	v_mul_f32_e32 v33, v33, v35
	v_cvt_pk_bf16_f32 v33, v33, s0
	ds_write_b16 v121, v33 offset:8192
	v_mul_f32_e32 v33, 0xbfb8aa3b, v32
	v_sub_f32_e32 v32, v223, v32
	v_mul_f32_e32 v32, 0x3fb8aa3b, v32
	v_exp_f32_e32 v33, v33
	v_exp_f32_e32 v32, v32
	v_mul_f32_e32 v33, v33, v34
	v_mul_f32_e32 v32, v32, v34
	v_cvt_pk_bf16_f32 v33, v33, s0
	v_cvt_pk_bf16_f32 v32, v32, s0
	ds_write_b16 v121, v33 offset:25600
	ds_write_b16 v118, v32 offset:43014
	v_add_f32_e32 v32, v212, v225
	v_mul_f32_e32 v35, 0x3fb8aa3b, v32
	v_exp_f32_e32 v35, v35
	v_lshlrev_b32_e32 v33, 16, v203
	v_mul_f32_e32 v33, 0x3db504f3, v33
	v_lshlrev_b32_e32 v34, 16, v193
	v_mul_f32_e32 v33, v33, v35
	v_cvt_pk_bf16_f32 v33, v33, s0
	ds_write_b16 v122, v33 offset:8192
	v_mul_f32_e32 v33, 0xbfb8aa3b, v32
	v_sub_f32_e32 v32, v223, v32
	v_mul_f32_e32 v32, 0x3fb8aa3b, v32
	v_exp_f32_e32 v33, v33
	v_exp_f32_e32 v32, v32
	v_mul_f32_e32 v33, v33, v34
	v_mul_f32_e32 v32, v32, v34
	v_cvt_pk_bf16_f32 v33, v33, s0
	v_cvt_pk_bf16_f32 v32, v32, s0
	ds_write_b16 v122, v33 offset:25600
	ds_write_b16 v118, v32 offset:43016
	v_add_f32_e32 v32, v213, v225
	v_mul_f32_e32 v35, 0x3fb8aa3b, v32
	v_exp_f32_e32 v35, v35
	v_lshlrev_b32_e32 v33, 16, v192
	v_mul_f32_e32 v33, 0x3db504f3, v33
	v_lshlrev_b32_e32 v34, 16, v191
	v_mul_f32_e32 v33, v33, v35
	v_cvt_pk_bf16_f32 v33, v33, s0
	ds_write_b16 v123, v33 offset:8192
	v_mul_f32_e32 v33, 0xbfb8aa3b, v32
	v_sub_f32_e32 v32, v223, v32
	v_mul_f32_e32 v32, 0x3fb8aa3b, v32
	v_exp_f32_e32 v33, v33
	v_exp_f32_e32 v32, v32
	v_mul_f32_e32 v33, v33, v34
	v_mul_f32_e32 v32, v32, v34
	v_cvt_pk_bf16_f32 v33, v33, s0
	v_cvt_pk_bf16_f32 v32, v32, s0
	ds_write_b16 v123, v33 offset:25600
	ds_write_b16 v118, v32 offset:43018
	v_add_f32_e32 v32, v214, v225
	v_mul_f32_e32 v35, 0x3fb8aa3b, v32
	v_exp_f32_e32 v35, v35
	v_lshlrev_b32_e32 v33, 16, v189
	v_mul_f32_e32 v33, 0x3db504f3, v33
	v_lshlrev_b32_e32 v34, 16, v190
	v_mul_f32_e32 v33, v33, v35
	v_cvt_pk_bf16_f32 v33, v33, s0
	ds_write_b16 v124, v33 offset:8192
	v_mul_f32_e32 v33, 0xbfb8aa3b, v32
	v_sub_f32_e32 v32, v223, v32
	v_mul_f32_e32 v32, 0x3fb8aa3b, v32
	v_exp_f32_e32 v33, v33
	v_exp_f32_e32 v32, v32
	v_mul_f32_e32 v33, v33, v34
	v_mul_f32_e32 v32, v32, v34
	v_cvt_pk_bf16_f32 v33, v33, s0
	v_cvt_pk_bf16_f32 v32, v32, s0
	ds_write_b16 v124, v33 offset:25600
	ds_write_b16 v118, v32 offset:43020
	v_add_f32_e32 v32, v215, v225
	v_mul_f32_e32 v35, 0x3fb8aa3b, v32
	v_exp_f32_e32 v35, v35
	v_lshlrev_b32_e32 v33, 16, v188
	v_mul_f32_e32 v33, 0x3db504f3, v33
	v_lshlrev_b32_e32 v34, 16, v187
	v_mul_f32_e32 v33, v33, v35
	v_cvt_pk_bf16_f32 v33, v33, s0
	ds_write_b16 v125, v33 offset:8192
	v_mul_f32_e32 v33, 0xbfb8aa3b, v32
	v_sub_f32_e32 v32, v223, v32
	v_mul_f32_e32 v32, 0x3fb8aa3b, v32
	v_exp_f32_e32 v33, v33
	v_exp_f32_e32 v32, v32
	v_mul_f32_e32 v33, v33, v34
	v_mul_f32_e32 v32, v32, v34
; DI float bf2f(bf16_t b) { return __uint_as_float(((unsigned)b) << 16); }
; DI void gla_item(const float* wgate, const float* bgate, const bf16_t* proj, bf16_t* mix, int item, LP unsigned char* lds3) {
;     ...
; #pragma unroll
;     for (int i = 0; i < 16; ++i) { const int t = tq * 16 + i; const float cum = pre + cl[i]; const float qf = bf2f(qv[i]), kf = bf2f(kv[i]);
;       Qd[t * 136 + d] = f2bf(qf * 0.08838834764831845f * __expf(cum));
;       Kd[t * 136 + d] = f2bf(kf * __expf(-cum));
;       KeT[d * 72 + t] = f2bf(kf * __expf(tot - cum)); }
;     if (tq == 0) dec[d] = __expf(tot);
	v_cvt_pk_bf16_f32 v33, v33, s0
	v_cvt_pk_bf16_f32 v32, v32, s0
	ds_write_b16 v125, v33 offset:25600
	ds_write_b16 v118, v32 offset:43022
	v_add_f32_e32 v32, v216, v225
	v_mul_f32_e32 v35, 0x3fb8aa3b, v32
	v_exp_f32_e32 v35, v35
	v_lshlrev_b32_e32 v33, 16, v186
	v_mul_f32_e32 v33, 0x3db504f3, v33
	v_lshlrev_b32_e32 v34, 16, v184
	v_mul_f32_e32 v33, v33, v35
	v_cvt_pk_bf16_f32 v33, v33, s0
	ds_write_b16 v126, v33 offset:8192
	v_mul_f32_e32 v33, 0xbfb8aa3b, v32
	v_sub_f32_e32 v32, v223, v32
	v_mul_f32_e32 v32, 0x3fb8aa3b, v32
	v_exp_f32_e32 v33, v33
	v_exp_f32_e32 v32, v32
	v_mul_f32_e32 v33, v33, v34
	v_mul_f32_e32 v32, v32, v34
	v_cvt_pk_bf16_f32 v33, v33, s0
	v_cvt_pk_bf16_f32 v32, v32, s0
	ds_write_b16 v126, v33 offset:25600
	ds_write_b16 v118, v32 offset:43024
	v_add_f32_e32 v32, v217, v225
	v_mul_f32_e32 v35, 0x3fb8aa3b, v32
	v_exp_f32_e32 v35, v35
	v_lshlrev_b32_e32 v33, 16, v183
	v_mul_f32_e32 v33, 0x3db504f3, v33
	v_lshlrev_b32_e32 v34, 16, v182
	v_mul_f32_e32 v33, v33, v35
	v_cvt_pk_bf16_f32 v33, v33, s0
	ds_write_b16 v127, v33 offset:8192
	v_mul_f32_e32 v33, 0xbfb8aa3b, v32
	v_sub_f32_e32 v32, v223, v32
	v_mul_f32_e32 v32, 0x3fb8aa3b, v32
	v_exp_f32_e32 v33, v33
	v_exp_f32_e32 v32, v32
	v_mul_f32_e32 v33, v33, v34
	v_mul_f32_e32 v32, v32, v34
	v_cvt_pk_bf16_f32 v33, v33, s0
	v_cvt_pk_bf16_f32 v32, v32, s0
	ds_write_b16 v127, v33 offset:25600
	ds_write_b16 v118, v32 offset:43026
	v_add_f32_e32 v32, v218, v225
	v_mul_f32_e32 v35, 0x3fb8aa3b, v32
	v_exp_f32_e32 v35, v35
	v_lshlrev_b32_e32 v33, 16, v46
	v_mul_f32_e32 v33, 0x3db504f3, v33
	v_lshlrev_b32_e32 v34, 16, v47
	v_mul_f32_e32 v33, v33, v35
	v_cvt_pk_bf16_f32 v33, v33, s0
	ds_write_b16 v128, v33 offset:8192
	v_mul_f32_e32 v33, 0xbfb8aa3b, v32
	v_sub_f32_e32 v32, v223, v32
	v_mul_f32_e32 v32, 0x3fb8aa3b, v32
	v_exp_f32_e32 v33, v33
	v_exp_f32_e32 v32, v32
	v_mul_f32_e32 v33, v33, v34
	v_mul_f32_e32 v32, v32, v34
	v_cvt_pk_bf16_f32 v33, v33, s0
	v_cvt_pk_bf16_f32 v32, v32, s0
	ds_write_b16 v128, v33 offset:25600
	ds_write_b16 v118, v32 offset:43028
	v_add_f32_e32 v32, v219, v225
	v_mul_f32_e32 v35, 0x3fb8aa3b, v32
	v_exp_f32_e32 v35, v35
	v_lshlrev_b32_e32 v33, 16, v45
	v_mul_f32_e32 v33, 0x3db504f3, v33
	v_lshlrev_b32_e32 v34, 16, v44
	v_mul_f32_e32 v33, v33, v35
	v_cvt_pk_bf16_f32 v33, v33, s0
	ds_write_b16 v129, v33 offset:8192
	v_mul_f32_e32 v33, 0xbfb8aa3b, v32
	v_sub_f32_e32 v32, v223, v32
	v_mul_f32_e32 v32, 0x3fb8aa3b, v32
	v_exp_f32_e32 v33, v33
	v_exp_f32_e32 v32, v32
	v_mul_f32_e32 v33, v33, v34
	v_mul_f32_e32 v32, v32, v34
	v_cvt_pk_bf16_f32 v33, v33, s0
	v_cvt_pk_bf16_f32 v32, v32, s0
	ds_write_b16 v129, v33 offset:25600
	ds_write_b16 v118, v32 offset:43030
	v_add_f32_e32 v32, v220, v225
	v_mul_f32_e32 v35, 0x3fb8aa3b, v32
	v_exp_f32_e32 v35, v35
	v_lshlrev_b32_e32 v33, 16, v43
	v_mul_f32_e32 v33, 0x3db504f3, v33
	v_lshlrev_b32_e32 v34, 16, v42
	v_mul_f32_e32 v33, v33, v35
	v_cvt_pk_bf16_f32 v33, v33, s0
	ds_write_b16 v130, v33 offset:8192
	v_mul_f32_e32 v33, 0xbfb8aa3b, v32
	v_sub_f32_e32 v32, v223, v32
	v_mul_f32_e32 v32, 0x3fb8aa3b, v32
	v_exp_f32_e32 v33, v33
	v_exp_f32_e32 v32, v32
	v_mul_f32_e32 v33, v33, v34
	v_mul_f32_e32 v32, v32, v34
	v_cvt_pk_bf16_f32 v33, v33, s0
	v_cvt_pk_bf16_f32 v32, v32, s0
	ds_write_b16 v130, v33 offset:25600
	ds_write_b16 v118, v32 offset:43032
	v_add_f32_e32 v32, v221, v225
	v_mul_f32_e32 v35, 0x3fb8aa3b, v32
	v_exp_f32_e32 v35, v35
	v_lshlrev_b32_e32 v33, 16, v41
	v_mul_f32_e32 v33, 0x3db504f3, v33
	v_lshlrev_b32_e32 v34, 16, v40
	v_mul_f32_e32 v33, v33, v35
	v_cvt_pk_bf16_f32 v33, v33, s0
	ds_write_b16 v131, v33 offset:8192
	v_mul_f32_e32 v33, 0xbfb8aa3b, v32
	v_sub_f32_e32 v32, v223, v32
	v_mul_f32_e32 v32, 0x3fb8aa3b, v32
	v_exp_f32_e32 v33, v33
	v_exp_f32_e32 v32, v32
	v_mul_f32_e32 v33, v33, v34
	v_mul_f32_e32 v32, v32, v34
	v_cvt_pk_bf16_f32 v33, v33, s0
	v_cvt_pk_bf16_f32 v32, v32, s0
	ds_write_b16 v131, v33 offset:25600
	ds_write_b16 v118, v32 offset:43034
	v_add_f32_e32 v32, v222, v225
	v_mul_f32_e32 v35, 0x3fb8aa3b, v32
	v_exp_f32_e32 v35, v35
	v_lshlrev_b32_e32 v33, 16, v39
	v_mul_f32_e32 v33, 0x3db504f3, v33
	v_lshlrev_b32_e32 v34, 16, v38
	v_mul_f32_e32 v33, v33, v35
	v_cvt_pk_bf16_f32 v33, v33, s0
	ds_write_b16 v132, v33 offset:8192
	v_mul_f32_e32 v33, 0xbfb8aa3b, v32
	v_sub_f32_e32 v32, v223, v32
	v_mul_f32_e32 v32, 0x3fb8aa3b, v32
	v_exp_f32_e32 v33, v33
	v_exp_f32_e32 v32, v32
	v_mul_f32_e32 v33, v33, v34
	v_mul_f32_e32 v32, v32, v34
	v_cvt_pk_bf16_f32 v33, v33, s0
	v_cvt_pk_bf16_f32 v32, v32, s0
	ds_write_b16 v132, v33 offset:25600
	ds_write_b16 v118, v32 offset:43036
	v_add_f32_e32 v32, v224, v225
	v_mul_f32_e32 v35, 0x3fb8aa3b, v32
	v_exp_f32_e32 v35, v35
	v_lshlrev_b32_e32 v33, 16, v37
	v_mul_f32_e32 v33, 0x3db504f3, v33
	v_lshlrev_b32_e32 v34, 16, v36
	v_mul_f32_e32 v33, v33, v35
	v_cvt_pk_bf16_f32 v33, v33, s0
	ds_write_b16 v133, v33 offset:8192
	v_mul_f32_e32 v33, 0xbfb8aa3b, v32
	v_sub_f32_e32 v32, v223, v32
	v_mul_f32_e32 v32, 0x3fb8aa3b, v32
	v_exp_f32_e32 v33, v33
	v_exp_f32_e32 v32, v32
	v_mul_f32_e32 v33, v33, v34
	v_mul_f32_e32 v32, v32, v34
	v_cvt_pk_bf16_f32 v33, v33, s0
	v_cvt_pk_bf16_f32 v32, v32, s0
	ds_write_b16 v133, v33 offset:25600
	ds_write_b16 v118, v32 offset:43038
	s_and_saveexec_b64 s[2:3], s[6:7]
	s_cbranch_execz .LBB0_654
	v_mul_f32_e32 v32, 0x3fb8aa3b, v223
	v_exp_f32_e32 v32, v32
	ds_write_b32 v108, v32 offset:6144
